# v53 + FFN1 accumulator zero-skip + fourier mid-row moved into the scan phase
# baseline (speedup 1.0000x reference)
; #define G8_STAGE(bufoff, gbase, voff) do { _Pragma("unroll") for (int _i = 0; _i < 2; ++_i) \
;         __builtin_amdgcn_global_load_lds((const unsigned*)((const char*)(gbase) + (voff)[_i]), (LAS unsigned*)(lds + (bufoff) + ldsw + _i * 8192), 16, 0, 0); } while (0)
; #define G8_LDA(dst, b, h) do { _Pragma("unroll") for (int m = 0; m < 4; ++m) _Pragma("unroll") for (int k = 0; k < 2; ++k) dst[m][k] = *(const LAS bf16x8*)(lds + G8_SA(b, h) + aoff + m * 2048 + k * 1024); } while (0)
; #define G8_LDB(dst, b, h) do { _Pragma("unroll") for (int n = 0; n < 2; ++n) _Pragma("unroll") for (int k = 0; k < 2; ++k) dst[n][k] = *(const LAS bf16x8*)(lds + G8_SB(b, h) + boff + n * 2048 + k * 1024); } while (0)
; #define G8_MMA(ai, bj, At, Bt) do { __builtin_amdgcn_s_setprio(1); _Pragma("unroll") for (int m = 0; m < 4; ++m) _Pragma("unroll") for (int n = 0; n < 2; ++n) _Pragma("unroll") for (int k = 0; k < 2; ++k) \
;         acc[ai][bj][m][n] = __builtin_amdgcn_mfma_f32_16x16x32_bf16(Bt[n][k], At[m][k], acc[ai][bj][m][n], 0, 0, 0); __builtin_amdgcn_s_setprio(0); } while (0)
; #define G8_WAIT_V(n) asm volatile("s_waitcnt vmcnt(" #n ")" ::: "memory")
; #define G8_WAIT_L(n) asm volatile("s_waitcnt lgkmcnt(" #n ")" ::: "memory")
; #define G8_BAR __builtin_amdgcn_s_barrier()
; template <class Epi, class Sched>
; __device__ __forceinline__ void gemm_phase(int wv, LAS unsigned char* lds, const int K, const Sched& S, const Epi& E) {
;     ...
;             const bool last = (t == nt - 2);
;             const char* a1 = cA + (size_t)(t + 1) * kstep;
;             const char* a2 = last ? nA : cA + (size_t)(t + 2) * kstep; const char* b2 = last ? nB : cB + (size_t)(t + 2) * kstep;
;             const char* a3 = a2 + kstep; const char* b3 = b2 + kstep;
;             G8_LDB(B0, 0, 0); G8_SCHED; G8_LDA(At, 0, 0); G8_STAGE(G8_SA(1, 1), a1 + hstep, voffA);
;             G8_WAIT_L(8); G8_BAR; G8_WAIT_L(0); G8_MMA(0, 0, At, B0); G8_BAR; G8_SCHED;
;             G8_LDB(B1, 0, 1); G8_STAGE(G8_SB(0, 0), b2, voffB);
;             G8_BAR; G8_WAIT_L(0); G8_MMA(0, 1, At, B1); G8_BAR;
;             if (full) G8_LDA(At, 0, 1); G8_STAGE(G8_SA(0, 0), a2, voffA);
;             G8_BAR; G8_WAIT_L(0); if (full) G8_MMA(1, 0, At, B0); G8_BAR; G8_SCHED;
;             G8_STAGE(G8_SB(0, 1), b2 + hstep, voffB);
;             G8_WAIT_V(6); G8_BAR; if (full) G8_MMA(1, 1, At, B1); G8_BAR;
.LBB0_1317:
	s_add_i32 s76, 0, 0x10000
	v_add_u32_e32 v0, s76, v220
	ds_read_b128 v[180:183], v0
	ds_read_b128 v[184:187], v0 offset:1024
	ds_read_b128 v[188:191], v0 offset:2048
	ds_read_b128 v[192:195], v0 offset:3072
	s_cmp_eq_u32 s75, 12
	s_cselect_b64 s[40:41], -1, 0
	s_and_b64 s[14:15], s[40:41], exec
	s_cselect_b32 s39, s29, s5
	s_cselect_b32 s38, s28, s4
	v_lshl_add_u64 v[2:3], s[36:37], 0, v[210:211]
	s_add_i32 m0, s42, 0xc000
	s_waitcnt lgkmcnt(0)
	ds_read_b128 v[144:147], v221
	ds_read_b128 v[160:163], v221 offset:1024
	ds_read_b128 v[140:143], v221 offset:2048
	ds_read_b128 v[156:159], v221 offset:3072
	ds_read_b128 v[136:139], v221 offset:4096
	ds_read_b128 v[152:155], v221 offset:5120
	ds_read_b128 v[132:135], v221 offset:6144
	ds_read_b128 v[148:151], v221 offset:7168
	global_load_lds_dwordx4 v[2:3], off
	v_lshl_add_u64 v[2:3], s[36:37], 0, v[212:213]
	s_add_i32 m0, s42, 0xe000
	s_nop 0
	global_load_lds_dwordx4 v[2:3], off
	s_waitcnt lgkmcnt(8)
	s_barrier
	s_waitcnt lgkmcnt(0)
	s_waitcnt lgkmcnt(0)
	s_cmp_eq_i32 s75, -2
	s_cbranch_scc1 .Lzk8_g0
	v_mfma_f32_16x16x32_bf16 v[124:127], v[180:183], v[144:147], v[124:127]
	v_mfma_f32_16x16x32_bf16 v[128:131], v[188:191], v[144:147], v[128:131]
	v_mfma_f32_16x16x32_bf16 v[108:111], v[180:183], v[140:143], v[108:111]
	v_mfma_f32_16x16x32_bf16 v[112:115], v[188:191], v[140:143], v[112:115]
	v_mfma_f32_16x16x32_bf16 v[92:95], v[180:183], v[136:139], v[92:95]
	v_mfma_f32_16x16x32_bf16 v[96:99], v[188:191], v[136:139], v[96:99]
	v_mfma_f32_16x16x32_bf16 v[76:79], v[180:183], v[132:135], v[76:79]
	v_mfma_f32_16x16x32_bf16 v[80:83], v[188:191], v[132:135], v[80:83]
	v_mfma_f32_16x16x32_bf16 v[124:127], v[184:187], v[160:163], v[124:127]
	v_mfma_f32_16x16x32_bf16 v[128:131], v[192:195], v[160:163], v[128:131]
	v_mfma_f32_16x16x32_bf16 v[108:111], v[184:187], v[156:159], v[108:111]
	v_mfma_f32_16x16x32_bf16 v[112:115], v[192:195], v[156:159], v[112:115]
	v_mfma_f32_16x16x32_bf16 v[92:95], v[184:187], v[152:155], v[92:95]
	v_mfma_f32_16x16x32_bf16 v[96:99], v[192:195], v[152:155], v[96:99]
	v_mfma_f32_16x16x32_bf16 v[76:79], v[184:187], v[148:151], v[76:79]
	v_mfma_f32_16x16x32_bf16 v[80:83], v[192:195], v[148:151], v[80:83]
.Lzk8_b0:
	s_barrier
	v_add_u32_e32 v0, 0, v220
	v_add_u32_e32 v2, 0x14000, v0
	s_add_i32 s14, s76, s3
	ds_read_b128 v[164:167], v2
	ds_read_b128 v[168:171], v2 offset:1024
	ds_read_b128 v[172:175], v2 offset:2048
	ds_read_b128 v[176:179], v2 offset:3072
	v_lshl_add_u64 v[2:3], s[38:39], 0, v[206:207]
	s_mov_b32 m0, s14
	v_lshl_add_u64 v[214:215], s[38:39], 0, v[208:209]
	global_load_lds_dwordx4 v[2:3], off
	s_add_i32 m0, s14, 0x2000
	s_nop 0
	global_load_lds_dwordx4 v[214:215], off
	s_barrier
	s_waitcnt lgkmcnt(0)
	s_waitcnt lgkmcnt(0)
	s_cmp_eq_i32 s75, -2
	s_cbranch_scc1 .Lzk8_g1
	v_mfma_f32_16x16x32_bf16 v[116:119], v[164:167], v[144:147], v[116:119]
	v_mfma_f32_16x16x32_bf16 v[120:123], v[172:175], v[144:147], v[120:123]
	v_mfma_f32_16x16x32_bf16 v[100:103], v[164:167], v[140:143], v[100:103]
	v_mfma_f32_16x16x32_bf16 v[104:107], v[172:175], v[140:143], v[104:107]
	v_mfma_f32_16x16x32_bf16 v[84:87], v[164:167], v[136:139], v[84:87]
	v_mfma_f32_16x16x32_bf16 v[88:91], v[172:175], v[136:139], v[88:91]
	v_mfma_f32_16x16x32_bf16 v[72:75], v[164:167], v[132:135], v[72:75]
	v_mfma_f32_16x16x32_bf16 v[68:71], v[172:175], v[132:135], v[68:71]
	v_mfma_f32_16x16x32_bf16 v[116:119], v[168:171], v[160:163], v[116:119]
	v_mfma_f32_16x16x32_bf16 v[120:123], v[176:179], v[160:163], v[120:123]
	v_mfma_f32_16x16x32_bf16 v[100:103], v[168:171], v[156:159], v[100:103]
	v_mfma_f32_16x16x32_bf16 v[104:107], v[176:179], v[156:159], v[104:107]
	v_mfma_f32_16x16x32_bf16 v[84:87], v[168:171], v[152:155], v[84:87]
	v_mfma_f32_16x16x32_bf16 v[88:91], v[176:179], v[152:155], v[88:91]
	v_mfma_f32_16x16x32_bf16 v[72:75], v[168:171], v[148:151], v[72:75]
	v_mfma_f32_16x16x32_bf16 v[68:71], v[176:179], v[148:151], v[68:71]
.Lzk8_b1:
	v_cndmask_b32_e64 v198, 0, 1, s[34:35]
	v_cmp_ne_u32_e64 s[14:15], 1, v198
	s_andn2_b64 vcc, exec, s[34:35]
	s_barrier
	s_cbranch_vccnz .LBB0_1319
	ds_read_b128 v[144:147], v221 offset:16384
	ds_read_b128 v[160:163], v221 offset:17408
	ds_read_b128 v[140:143], v221 offset:18432
	ds_read_b128 v[156:159], v221 offset:19456
	ds_read_b128 v[136:139], v221 offset:20480
	ds_read_b128 v[152:155], v221 offset:21504
	ds_read_b128 v[132:135], v221 offset:22528
	ds_read_b128 v[148:151], v221 offset:23552
.LBB0_1319:
	s_add_u32 s76, s36, 0xfffc0080
	s_addc_u32 s77, s37, -1
	s_and_b64 s[40:41], s[40:41], exec
	s_cselect_b32 s41, s27, s77
	s_cselect_b32 s40, s26, s76
	s_mov_b32 m0, s42
	v_lshl_add_u64 v[216:217], s[40:41], 0, v[206:207]
	global_load_lds_dwordx4 v[216:217], off
	v_lshl_add_u64 v[218:219], s[40:41], 0, v[208:209]
	s_mov_b32 m0, s43
	s_and_b64 vcc, exec, s[14:15]
	global_load_lds_dwordx4 v[218:219], off
	s_barrier
	s_waitcnt lgkmcnt(0)
	s_cbranch_vccnz .LBB0_1321
	s_waitcnt lgkmcnt(0)
	s_cmp_eq_i32 s75, -2
	s_cbranch_scc1 .Lzk8_g2
	v_mfma_f32_16x16x32_bf16 v[60:63], v[180:183], v[144:147], v[60:63]
	v_mfma_f32_16x16x32_bf16 v[64:67], v[188:191], v[144:147], v[64:67]
	v_mfma_f32_16x16x32_bf16 v[44:47], v[180:183], v[140:143], v[44:47]
	v_mfma_f32_16x16x32_bf16 v[48:51], v[188:191], v[140:143], v[48:51]
	v_mfma_f32_16x16x32_bf16 v[28:31], v[180:183], v[136:139], v[28:31]
	v_mfma_f32_16x16x32_bf16 v[32:35], v[188:191], v[136:139], v[32:35]
	v_mfma_f32_16x16x32_bf16 v[12:15], v[180:183], v[132:135], v[12:15]
	v_mfma_f32_16x16x32_bf16 v[16:19], v[188:191], v[132:135], v[16:19]
	v_mfma_f32_16x16x32_bf16 v[60:63], v[184:187], v[160:163], v[60:63]
	v_mfma_f32_16x16x32_bf16 v[64:67], v[192:195], v[160:163], v[64:67]
	v_mfma_f32_16x16x32_bf16 v[44:47], v[184:187], v[156:159], v[44:47]
	v_mfma_f32_16x16x32_bf16 v[48:51], v[192:195], v[156:159], v[48:51]
	v_mfma_f32_16x16x32_bf16 v[28:31], v[184:187], v[152:155], v[28:31]
	v_mfma_f32_16x16x32_bf16 v[32:35], v[192:195], v[152:155], v[32:35]
	v_mfma_f32_16x16x32_bf16 v[12:15], v[184:187], v[148:151], v[12:15]
	v_mfma_f32_16x16x32_bf16 v[16:19], v[192:195], v[148:151], v[16:19]
.Lzk8_b2:
.LBB0_1321:
	s_barrier
	s_add_u32 s76, s38, 0x40000
	s_addc_u32 s77, s39, 0
	s_mov_b32 m0, s46
	v_lshl_add_u64 v[180:181], s[76:77], 0, v[206:207]
	global_load_lds_dwordx4 v[180:181], off
	v_lshl_add_u64 v[180:181], s[76:77], 0, v[208:209]
	s_mov_b32 m0, s47
	s_and_b64 vcc, exec, s[14:15]
	global_load_lds_dwordx4 v[180:181], off
	s_cmp_eq_u32 s101, 1
	s_cbranch_scc1 .Lp8rx_a
	s_waitcnt vmcnt(6)
	s_branch .Lp8rx_b

; #define G8_STAGE(bufoff, gbase, voff) do { _Pragma("unroll") for (int _i = 0; _i < 2; ++_i) \
;         __builtin_amdgcn_global_load_lds((const unsigned*)((const char*)(gbase) + (voff)[_i]), (LAS unsigned*)(lds + (bufoff) + ldsw + _i * 8192), 16, 0, 0); } while (0)
; #define G8_LDA(dst, b, h) do { _Pragma("unroll") for (int m = 0; m < 4; ++m) _Pragma("unroll") for (int k = 0; k < 2; ++k) dst[m][k] = *(const LAS bf16x8*)(lds + G8_SA(b, h) + aoff + m * 2048 + k * 1024); } while (0)
; #define G8_LDB(dst, b, h) do { _Pragma("unroll") for (int n = 0; n < 2; ++n) _Pragma("unroll") for (int k = 0; k < 2; ++k) dst[n][k] = *(const LAS bf16x8*)(lds + G8_SB(b, h) + boff + n * 2048 + k * 1024); } while (0)
; #define G8_MMA(ai, bj, At, Bt) do { __builtin_amdgcn_s_setprio(1); _Pragma("unroll") for (int m = 0; m < 4; ++m) _Pragma("unroll") for (int n = 0; n < 2; ++n) _Pragma("unroll") for (int k = 0; k < 2; ++k) \
;         acc[ai][bj][m][n] = __builtin_amdgcn_mfma_f32_16x16x32_bf16(Bt[n][k], At[m][k], acc[ai][bj][m][n], 0, 0, 0); __builtin_amdgcn_s_setprio(0); } while (0)
; #define G8_WAIT_V(n) asm volatile("s_waitcnt vmcnt(" #n ")" ::: "memory")
; #define G8_WAIT_L(n) asm volatile("s_waitcnt lgkmcnt(" #n ")" ::: "memory")
; #define G8_BAR __builtin_amdgcn_s_barrier()
; #define G8_SCHED __builtin_amdgcn_sched_barrier(0)
; template <class Epi, class Sched>
; __device__ __forceinline__ void gemm_phase(int wv, LAS unsigned char* lds, const int K, const Sched& S, const Epi& E) {
;     ...
;             G8_WAIT_V(6); G8_BAR; if (full) G8_MMA(1, 1, At, B1); G8_BAR;
;             G8_LDB(B0, 1, 0); G8_SCHED; G8_LDA(At, 1, 0); G8_STAGE(G8_SA(0, 1), a2 + hstep, voffA);
;             G8_WAIT_L(8); G8_BAR; G8_WAIT_L(0); G8_MMA(0, 0, At, B0); G8_BAR; G8_SCHED;
;             G8_LDB(B1, 1, 1); G8_STAGE(G8_SB(1, 0), b3, voffB);
;             G8_BAR; G8_WAIT_L(0); G8_MMA(0, 1, At, B1); G8_BAR;
.Lp8rx_b:
	s_barrier
	s_cbranch_vccnz .LBB0_1323
	s_waitcnt lgkmcnt(0)
	s_cmp_eq_i32 s75, -2
	s_cbranch_scc1 .Lzk8_g3
	v_mfma_f32_16x16x32_bf16 v[52:55], v[164:167], v[144:147], v[52:55]
	v_mfma_f32_16x16x32_bf16 v[56:59], v[172:175], v[144:147], v[56:59]
	v_mfma_f32_16x16x32_bf16 v[36:39], v[164:167], v[140:143], v[36:39]
	v_mfma_f32_16x16x32_bf16 v[40:43], v[172:175], v[140:143], v[40:43]
	v_mfma_f32_16x16x32_bf16 v[20:23], v[164:167], v[136:139], v[20:23]
	v_mfma_f32_16x16x32_bf16 v[24:27], v[172:175], v[136:139], v[24:27]
	v_mfma_f32_16x16x32_bf16 v[4:7], v[164:167], v[132:135], v[4:7]
	v_mfma_f32_16x16x32_bf16 v[8:11], v[172:175], v[132:135], v[8:11]
	v_mfma_f32_16x16x32_bf16 v[52:55], v[168:171], v[160:163], v[52:55]
	v_mfma_f32_16x16x32_bf16 v[56:59], v[176:179], v[160:163], v[56:59]
	v_mfma_f32_16x16x32_bf16 v[36:39], v[168:171], v[156:159], v[36:39]
	v_mfma_f32_16x16x32_bf16 v[40:43], v[176:179], v[156:159], v[40:43]
	v_mfma_f32_16x16x32_bf16 v[20:23], v[168:171], v[152:155], v[20:23]
	v_mfma_f32_16x16x32_bf16 v[24:27], v[176:179], v[152:155], v[24:27]
	v_mfma_f32_16x16x32_bf16 v[4:7], v[168:171], v[148:151], v[4:7]
	v_mfma_f32_16x16x32_bf16 v[8:11], v[176:179], v[148:151], v[8:11]
.Lzk8_b3:
.LBB0_1323:
	s_add_i32 s76, 0, 0x18000
	s_waitcnt lgkmcnt(0)
	v_add_u32_e32 v132, s76, v220
	s_barrier
	ds_read_b128 v[180:183], v132
	ds_read_b128 v[184:187], v132 offset:1024
	ds_read_b128 v[188:191], v132 offset:2048
	ds_read_b128 v[192:195], v132 offset:3072
	s_add_u32 s40, s40, 0x40000
	s_addc_u32 s41, s41, 0
	s_mov_b32 m0, s48
	v_lshl_add_u64 v[164:165], s[40:41], 0, v[206:207]
	ds_read_b128 v[144:147], v221 offset:32768
	ds_read_b128 v[160:163], v221 offset:33792
	ds_read_b128 v[140:143], v221 offset:34816
	ds_read_b128 v[156:159], v221 offset:35840
	ds_read_b128 v[136:139], v221 offset:36864
	ds_read_b128 v[152:155], v221 offset:37888
	ds_read_b128 v[132:135], v221 offset:38912
	ds_read_b128 v[148:151], v221 offset:39936
	global_load_lds_dwordx4 v[164:165], off
	v_lshl_add_u64 v[164:165], s[40:41], 0, v[208:209]
	s_mov_b32 m0, s49
	s_nop 0
	global_load_lds_dwordx4 v[164:165], off
	s_waitcnt lgkmcnt(8)
	s_barrier
	s_waitcnt lgkmcnt(0)
	s_waitcnt lgkmcnt(0)
	v_mfma_f32_16x16x32_bf16 v[124:127], v[180:183], v[144:147], v[124:127]
	v_mfma_f32_16x16x32_bf16 v[128:131], v[188:191], v[144:147], v[128:131]
	v_mfma_f32_16x16x32_bf16 v[108:111], v[180:183], v[140:143], v[108:111]
	v_mfma_f32_16x16x32_bf16 v[112:115], v[188:191], v[140:143], v[112:115]
	v_mfma_f32_16x16x32_bf16 v[92:95], v[180:183], v[136:139], v[92:95]
	v_mfma_f32_16x16x32_bf16 v[96:99], v[188:191], v[136:139], v[96:99]
	v_mfma_f32_16x16x32_bf16 v[76:79], v[180:183], v[132:135], v[76:79]
	v_mfma_f32_16x16x32_bf16 v[80:83], v[188:191], v[132:135], v[80:83]
	v_mfma_f32_16x16x32_bf16 v[124:127], v[184:187], v[160:163], v[124:127]
	v_mfma_f32_16x16x32_bf16 v[128:131], v[192:195], v[160:163], v[128:131]
	v_mfma_f32_16x16x32_bf16 v[108:111], v[184:187], v[156:159], v[108:111]
	v_mfma_f32_16x16x32_bf16 v[112:115], v[192:195], v[156:159], v[112:115]
	v_mfma_f32_16x16x32_bf16 v[92:95], v[184:187], v[152:155], v[92:95]
	v_mfma_f32_16x16x32_bf16 v[96:99], v[192:195], v[152:155], v[96:99]
	v_mfma_f32_16x16x32_bf16 v[76:79], v[184:187], v[148:151], v[76:79]
	v_mfma_f32_16x16x32_bf16 v[80:83], v[192:195], v[148:151], v[80:83]
	s_barrier
	s_add_i32 s40, s76, s3
	v_add_u32_e32 v0, 0x1c000, v0
	v_lshl_add_u64 v[2:3], v[2:3], 0, s[58:59]
	s_mov_b32 m0, s40
	ds_read_b128 v[164:167], v0
	ds_read_b128 v[168:171], v0 offset:1024
	ds_read_b128 v[172:175], v0 offset:2048
	ds_read_b128 v[176:179], v0 offset:3072
	global_load_lds_dwordx4 v[2:3], off
	v_lshl_add_u64 v[2:3], v[214:215], 0, s[58:59]
	s_add_i32 m0, s40, 0x2000
	s_nop 0
	global_load_lds_dwordx4 v[2:3], off
	s_barrier
	s_waitcnt lgkmcnt(0)
	s_waitcnt lgkmcnt(0)
	v_mfma_f32_16x16x32_bf16 v[116:119], v[164:167], v[144:147], v[116:119]
	v_mfma_f32_16x16x32_bf16 v[120:123], v[172:175], v[144:147], v[120:123]
	v_mfma_f32_16x16x32_bf16 v[100:103], v[164:167], v[140:143], v[100:103]
	v_mfma_f32_16x16x32_bf16 v[104:107], v[172:175], v[140:143], v[104:107]
	v_mfma_f32_16x16x32_bf16 v[84:87], v[164:167], v[136:139], v[84:87]
	v_mfma_f32_16x16x32_bf16 v[88:91], v[172:175], v[136:139], v[88:91]
	v_mfma_f32_16x16x32_bf16 v[72:75], v[164:167], v[132:135], v[72:75]
	v_mfma_f32_16x16x32_bf16 v[68:71], v[172:175], v[132:135], v[68:71]
	v_mfma_f32_16x16x32_bf16 v[116:119], v[168:171], v[160:163], v[116:119]
	v_mfma_f32_16x16x32_bf16 v[120:123], v[176:179], v[160:163], v[120:123]
	v_mfma_f32_16x16x32_bf16 v[100:103], v[168:171], v[156:159], v[100:103]
	v_mfma_f32_16x16x32_bf16 v[104:107], v[176:179], v[156:159], v[104:107]
	v_mfma_f32_16x16x32_bf16 v[84:87], v[168:171], v[152:155], v[84:87]
	v_mfma_f32_16x16x32_bf16 v[88:91], v[176:179], v[152:155], v[88:91]
	v_mfma_f32_16x16x32_bf16 v[72:75], v[168:171], v[148:151], v[72:75]
	v_mfma_f32_16x16x32_bf16 v[68:71], v[176:179], v[148:151], v[68:71]
	s_cmp_eq_u32 s101, 1
	s_cbranch_scc0 .Lp8rx_c
	s_waitcnt vmcnt(10)
